# GEMM K-loop: first K-pair after a tile epilogue skips the two vmcnt(8) waits that only drained the epilogue stores (needed LDS-DMA loads already complete)
# speedup vs baseline: 1.0062x; 1.0027x over previous
.LBB0_376:
	s_mov_b32 s98, 0
	s_add_i32 s68, s25, 0x18000
	v_lshl_add_u64 v[8:9], v[8:9], 0, s[90:91]
	s_mov_b32 m0, s68
	s_add_i32 s69, s25, 0x1a000
	s_waitcnt vmcnt(2)
	s_barrier
	global_load_lds_dwordx4 v[8:9], off
	v_lshl_add_u64 v[4:5], v[4:5], 0, s[90:91]
	s_mov_b32 m0, s69
	s_add_i32 s73, s25, 0x8000
	global_load_lds_dwordx4 v[4:5], off
	v_lshl_add_u64 v[4:5], v[6:7], 0, s[90:91]
	s_mov_b32 m0, s73
	s_add_i32 s34, s25, 0xa000
	global_load_lds_dwordx4 v[4:5], off
	v_lshl_add_u64 v[4:5], v[10:11], 0, s[90:91]
	s_mov_b32 m0, s34
	s_add_i32 s35, s25, 0x1c000
	global_load_lds_dwordx4 v[4:5], off
	v_lshl_add_u64 v[2:3], v[2:3], 0, s[90:91]
	s_mov_b32 m0, s35
	s_add_i32 s14, s25, 0x1e000
	global_load_lds_dwordx4 v[2:3], off
	v_lshl_add_u64 v[0:1], v[0:1], 0, s[90:91]
	s_mov_b32 m0, s14
	v_bfe_u32 v19, v12, 4, 2
	global_load_lds_dwordx4 v[0:1], off
	s_lshl_b32 s6, s6, 5
	v_and_b32_e32 v239, 15, v12
	v_lshlrev_b32_e32 v20, 4, v19
	v_lshlrev_b32_e32 v12, 2, v12
	s_and_b32 s8, s6, 0x60
	s_lshl_b32 s16, s7, 6
	v_lshl_or_b32 v20, v239, 6, v20
	s_lshl_b32 s7, s7, 13
	v_and_b32_e32 v12, 32, v12
	s_lshl_b32 s6, s8, 7
	s_lshr_b32 s44, s82, 6
	v_bitop3_b32 v21, v20, s7, v12 bitop3:0xde
	v_bitop3_b32 v12, v20, s6, v12 bitop3:0xde
	s_mov_b32 s6, s82
	s_add_i32 s17, s44, -2
	v_writelane_b32 v254, s6, 45
	s_cmpk_lt_u32 s28, 0x100
	s_cselect_b64 s[70:71], -1, 0
	v_writelane_b32 v254, s7, 46
	v_lshl_or_b32 v240, v19, 3, s8
	s_add_u32 s8, s20, 0x1d00000
	v_writelane_b32 v254, s8, 26
	s_addc_u32 s8, s21, 0
	v_writelane_b32 v254, s8, 27
	s_add_u32 s8, s20, 0x1400000
	s_addc_u32 s9, s21, 0
	v_writelane_b32 v254, s8, 43
	v_add_u32_e32 v0, v15, v13
	s_waitcnt vmcnt(6)
	v_add_lshl_u32 v192, v0, v14, 1
	v_writelane_b32 v254, s9, 44
	s_add_u32 s8, s20, 0x1500000
	v_writelane_b32 v254, s8, 34
	s_addc_u32 s8, s21, 0
	s_cmp_lg_u64 s[46:47], 0
	v_writelane_b32 v254, s8, 35
	s_cselect_b64 s[8:9], -1, 0
	v_writelane_b32 v254, s8, 30
	v_add_u32_e32 v0, v18, v16
	v_cmp_eq_u32_e64 s[6:7], 0, v19
	v_writelane_b32 v254, s9, 31
	v_add_u32_e32 v241, 0, v12
	v_readlane_b32 s8, v254, 63
	v_readlane_b32 s9, v255, 0
	s_cmp_lg_u64 s[8:9], 0
	s_cselect_b64 s[8:9], -1, 0
	v_writelane_b32 v254, s8, 14
	v_add_u32_e32 v242, 0, v21
	v_readlane_b32 s45, v253, 40
	v_writelane_b32 v254, s9, 15
	s_add_u32 s8, s66, 0x80
	s_addc_u32 s9, s67, 0
	v_lshl_add_u64 v[202:203], s[8:9], 0, v[192:193]
	v_add_lshl_u32 v192, v0, v17, 1
	v_mov_b32_e32 v0, 0
	v_lshl_add_u64 v[204:205], s[8:9], 0, v[192:193]
	v_readlane_b32 s52, v253, 0
	v_mov_b32_e32 v1, v0
	v_mov_b32_e32 v2, v0
	v_mov_b32_e32 v3, v0
	v_mov_b32_e32 v4, v0
	v_mov_b32_e32 v5, v0
	v_mov_b32_e32 v6, v0
	v_mov_b32_e32 v7, v0
	v_mov_b32_e32 v8, v0
	v_mov_b32_e32 v9, v0
	v_mov_b32_e32 v10, v0
	v_mov_b32_e32 v11, v0
	v_mov_b32_e32 v12, v0
	v_mov_b32_e32 v13, v0
	v_mov_b32_e32 v14, v0
	v_mov_b32_e32 v15, v0
	v_mov_b32_e32 v16, v0
	v_mov_b32_e32 v17, v0
	v_mov_b32_e32 v18, v0
	v_mov_b32_e32 v19, v0
	v_mov_b32_e32 v20, v0
	v_mov_b32_e32 v21, v0
	v_mov_b32_e32 v22, v0
	v_mov_b32_e32 v23, v0
	v_mov_b32_e32 v24, v0
	v_mov_b32_e32 v25, v0
	v_mov_b32_e32 v26, v0
	v_mov_b32_e32 v27, v0
	v_mov_b32_e32 v28, v0
	v_mov_b32_e32 v29, v0
	v_mov_b32_e32 v30, v0
	v_mov_b32_e32 v31, v0
	v_mov_b32_e32 v32, v0
	v_mov_b32_e32 v33, v0
	v_mov_b32_e32 v34, v0
	v_mov_b32_e32 v35, v0
	v_mov_b32_e32 v36, v0
	v_mov_b32_e32 v37, v0
	v_mov_b32_e32 v38, v0
	v_mov_b32_e32 v39, v0
	v_mov_b32_e32 v40, v0
	v_mov_b32_e32 v41, v0
	v_mov_b32_e32 v42, v0
	v_mov_b32_e32 v43, v0
	v_mov_b32_e32 v44, v0
	v_mov_b32_e32 v45, v0
	v_mov_b32_e32 v46, v0
	v_mov_b32_e32 v47, v0
	v_mov_b32_e32 v48, v0
	v_mov_b32_e32 v49, v0
	v_mov_b32_e32 v50, v0
	v_mov_b32_e32 v51, v0
	v_mov_b32_e32 v56, v0
	v_mov_b32_e32 v57, v0
	v_mov_b32_e32 v58, v0
	v_mov_b32_e32 v59, v0
	v_mov_b32_e32 v64, v0
	v_mov_b32_e32 v65, v0
	v_mov_b32_e32 v66, v0
	v_mov_b32_e32 v67, v0
	v_mov_b32_e32 v72, v0
	v_mov_b32_e32 v73, v0
	v_mov_b32_e32 v74, v0
	v_mov_b32_e32 v75, v0
	v_mov_b32_e32 v80, v0
	v_mov_b32_e32 v81, v0
	v_mov_b32_e32 v82, v0
	v_mov_b32_e32 v83, v0
	v_mov_b32_e32 v88, v0
	v_mov_b32_e32 v89, v0
	v_mov_b32_e32 v90, v0
	v_mov_b32_e32 v91, v0
	v_mov_b32_e32 v96, v0
	v_mov_b32_e32 v97, v0
	v_mov_b32_e32 v98, v0
	v_mov_b32_e32 v99, v0
	v_mov_b32_e32 v104, v0
	v_mov_b32_e32 v105, v0
	v_mov_b32_e32 v106, v0
	v_mov_b32_e32 v107, v0
	v_mov_b32_e32 v52, v0
	v_mov_b32_e32 v53, v0
	v_mov_b32_e32 v54, v0
	v_mov_b32_e32 v55, v0
	v_mov_b32_e32 v60, v0
	v_mov_b32_e32 v61, v0
	v_mov_b32_e32 v62, v0
	v_mov_b32_e32 v63, v0
	v_mov_b32_e32 v68, v0
	v_mov_b32_e32 v69, v0
	v_mov_b32_e32 v70, v0
	v_mov_b32_e32 v71, v0
	v_mov_b32_e32 v76, v0
	v_mov_b32_e32 v77, v0
	v_mov_b32_e32 v78, v0
	v_mov_b32_e32 v79, v0
	v_mov_b32_e32 v84, v0
	v_mov_b32_e32 v85, v0
	v_mov_b32_e32 v86, v0
	v_mov_b32_e32 v87, v0
	v_mov_b32_e32 v92, v0
	v_mov_b32_e32 v93, v0
	v_mov_b32_e32 v94, v0
	v_mov_b32_e32 v95, v0
	v_mov_b32_e32 v100, v0
	v_mov_b32_e32 v101, v0
	v_mov_b32_e32 v102, v0
	v_mov_b32_e32 v103, v0
	v_mov_b32_e32 v108, v0
	v_mov_b32_e32 v109, v0
	v_mov_b32_e32 v110, v0
	v_mov_b32_e32 v111, v0
	v_mov_b32_e32 v112, v0
	v_mov_b32_e32 v113, v0
	v_mov_b32_e32 v114, v0
	v_mov_b32_e32 v115, v0
	v_mov_b32_e32 v116, v0
	v_mov_b32_e32 v117, v0
	v_mov_b32_e32 v118, v0
	v_mov_b32_e32 v119, v0
	v_mov_b32_e32 v120, v0
	v_mov_b32_e32 v121, v0
	v_mov_b32_e32 v122, v0
	v_mov_b32_e32 v123, v0
	v_mov_b32_e32 v124, v0
	v_mov_b32_e32 v125, v0
	v_mov_b32_e32 v126, v0
	v_mov_b32_e32 v127, v0
	s_barrier
	s_branch .LBB0_379
.LBB0_377:
	s_mov_b32 s98, 0
	s_cmp_lt_i32 s29, 1
	s_cbranch_scc1 .Lkf_done
	s_cmp_gt_i32 s29, 5
	s_cbranch_scc1 .Lkf_done
	s_mov_b32 s98, 1

.LBB0_442:
	s_cmp_eq_u32 s17, s53
	v_add_u32_e32 v128, 0x10000, v241
	v_add_u32_e32 v140, 0x14000, v241
	s_cselect_b64 s[12:13], -1, 0
	s_add_u32 s40, s60, s10
	s_waitcnt lgkmcnt(0)
	ds_read_b128 v[144:147], v128
	ds_read_b128 v[148:151], v128 offset:1024
	ds_read_b128 v[152:155], v128 offset:2048
	ds_read_b128 v[156:159], v128 offset:3072
	ds_read_b128 v[128:131], v140
	ds_read_b128 v[132:135], v140 offset:1024
	ds_read_b128 v[136:139], v140 offset:2048
	ds_read_b128 v[140:143], v140 offset:3072
	s_addc_u32 s41, s61, s11
	s_and_b64 s[8:9], s[12:13], exec
	s_cselect_b32 s43, s85, s41
	s_cselect_b32 s42, s84, s40
	s_add_u32 s50, s62, s10
	s_addc_u32 s51, s63, s11
	s_and_b64 s[8:9], s[78:79], s[12:13]
	s_and_b64 s[12:13], s[12:13], exec
	s_mov_b64 s[40:41], -1
	s_cselect_b32 s13, s87, s51
	s_cselect_b32 s12, s86, s50
	v_lshl_add_u64 v[210:211], s[60:61], 0, v[208:209]
	s_add_i32 m0, s25, 0xc000
	ds_read_b128 v[160:163], v242
	ds_read_b128 v[164:167], v242 offset:1024
	ds_read_b128 v[168:171], v242 offset:2048
	ds_read_b128 v[172:175], v242 offset:3072
	ds_read_b128 v[176:179], v242 offset:4096
	ds_read_b128 v[180:183], v242 offset:5120
	ds_read_b128 v[184:187], v242 offset:6144
	ds_read_b128 v[188:191], v242 offset:7168
	global_load_lds_dwordx4 v[210:211], off
	v_lshl_add_u64 v[210:211], s[60:61], 0, v[206:207]
	s_add_i32 m0, s25, 0xe000
	s_nop 0
	global_load_lds_dwordx4 v[210:211], off
	s_cmp_lg_u32 s98, 0
	s_cbranch_scc1 .Lkw1
	s_waitcnt vmcnt(8)
.Lkw1:
	s_waitcnt lgkmcnt(0)
	s_barrier
	s_setprio 1
	s_waitcnt lgkmcnt(0)
	v_mfma_f32_16x16x32_bf16 v[104:107], v[144:147], v[160:163], v[104:107]
	v_mfma_f32_16x16x32_bf16 v[96:99], v[152:155], v[160:163], v[96:99]
	v_mfma_f32_16x16x32_bf16 v[88:91], v[144:147], v[168:171], v[88:91]
	v_mfma_f32_16x16x32_bf16 v[80:83], v[152:155], v[168:171], v[80:83]
	v_mfma_f32_16x16x32_bf16 v[72:75], v[144:147], v[176:179], v[72:75]
	v_mfma_f32_16x16x32_bf16 v[64:67], v[152:155], v[176:179], v[64:67]
	v_mfma_f32_16x16x32_bf16 v[56:59], v[144:147], v[184:187], v[56:59]
	v_mfma_f32_16x16x32_bf16 v[48:51], v[152:155], v[184:187], v[48:51]
	v_mfma_f32_16x16x32_bf16 v[104:107], v[148:151], v[164:167], v[104:107]
	v_mfma_f32_16x16x32_bf16 v[96:99], v[156:159], v[164:167], v[96:99]
	v_mfma_f32_16x16x32_bf16 v[88:91], v[148:151], v[172:175], v[88:91]
	v_mfma_f32_16x16x32_bf16 v[80:83], v[156:159], v[172:175], v[80:83]
	v_mfma_f32_16x16x32_bf16 v[72:75], v[148:151], v[180:183], v[72:75]
	v_mfma_f32_16x16x32_bf16 v[64:67], v[156:159], v[180:183], v[64:67]
	v_mfma_f32_16x16x32_bf16 v[56:59], v[148:151], v[188:191], v[56:59]
	v_mfma_f32_16x16x32_bf16 v[48:51], v[156:159], v[188:191], v[48:51]
	s_setprio 0
	s_setprio 1
	v_mfma_f32_16x16x32_bf16 v[44:47], v[128:131], v[160:163], v[44:47]
	v_mfma_f32_16x16x32_bf16 v[40:43], v[136:139], v[160:163], v[40:43]
	v_mfma_f32_16x16x32_bf16 v[36:39], v[128:131], v[168:171], v[36:39]
	v_mfma_f32_16x16x32_bf16 v[32:35], v[136:139], v[168:171], v[32:35]
	v_mfma_f32_16x16x32_bf16 v[28:31], v[128:131], v[176:179], v[28:31]
	v_mfma_f32_16x16x32_bf16 v[24:27], v[136:139], v[176:179], v[24:27]
	v_mfma_f32_16x16x32_bf16 v[20:23], v[128:131], v[184:187], v[20:23]
	v_mfma_f32_16x16x32_bf16 v[16:19], v[136:139], v[184:187], v[16:19]
	v_mfma_f32_16x16x32_bf16 v[44:47], v[132:135], v[164:167], v[44:47]
	v_mfma_f32_16x16x32_bf16 v[40:43], v[140:143], v[164:167], v[40:43]
	v_mfma_f32_16x16x32_bf16 v[36:39], v[132:135], v[172:175], v[36:39]
	v_mfma_f32_16x16x32_bf16 v[32:35], v[140:143], v[172:175], v[32:35]
	v_mfma_f32_16x16x32_bf16 v[28:31], v[132:135], v[180:183], v[28:31]
	v_mfma_f32_16x16x32_bf16 v[24:27], v[140:143], v[180:183], v[24:27]
	v_mfma_f32_16x16x32_bf16 v[20:23], v[132:135], v[188:191], v[20:23]
	v_mfma_f32_16x16x32_bf16 v[16:19], v[140:143], v[188:191], v[16:19]
	s_setprio 0
	s_barrier
	ds_read_b128 v[184:187], v242 offset:16384
	ds_read_b128 v[188:191], v242 offset:17408
	ds_read_b128 v[176:179], v242 offset:18432
	ds_read_b128 v[180:183], v242 offset:19456
	ds_read_b128 v[168:171], v242 offset:20480
	ds_read_b128 v[172:175], v242 offset:21504
	ds_read_b128 v[160:163], v242 offset:22528
	ds_read_b128 v[164:167], v242 offset:23552
	s_and_b64 vcc, exec, s[8:9]
	v_lshl_add_u64 v[216:217], s[12:13], 0, v[196:197]
	v_lshl_add_u64 v[214:215], s[12:13], 0, v[200:201]
	v_lshl_add_u64 v[212:213], s[42:43], 0, v[194:195]
	v_lshl_add_u64 v[210:211], s[42:43], 0, v[198:199]
	s_cbranch_vccnz .LBB0_444
	s_mov_b32 m0, s74
	s_add_u32 s40, s12, s66
	global_load_lds_dwordx4 v[216:217], off
	s_mov_b32 m0, s75
	s_addc_u32 s41, s13, s67
	global_load_lds_dwordx4 v[214:215], off
	v_lshl_add_u64 v[218:219], s[40:41], 0, v[196:197]
	s_mov_b32 m0, s2
	s_nop 0
	global_load_lds_dwordx4 v[218:219], off
	v_lshl_add_u64 v[218:219], s[40:41], 0, v[200:201]
	s_mov_b32 m0, s3
	s_mov_b64 s[40:41], 0
	global_load_lds_dwordx4 v[218:219], off
	s_mov_b32 m0, s25
	s_nop 0
	global_load_lds_dwordx4 v[212:213], off
	s_mov_b32 m0, s31
	s_nop 0
	global_load_lds_dwordx4 v[210:211], off
	s_cmp_lg_u32 s98, 0
	s_cbranch_scc1 .Lkw2
	s_waitcnt vmcnt(8)
.Lkw2:
	s_mov_b32 s98, 0
